# grid barrier: only each XCD leader does the device-scope buffer_inv (completed before it republishes the generation); the other workgroups invalidate their L1 only (buffer_inv sc0)
# speedup vs baseline: 1.0193x; 1.0110x over previous
.LBB0_837:
	s_or_b64 exec, exec, s[28:29]
	s_waitcnt vmcnt(0)
	buffer_inv sc0
	s_waitcnt vmcnt(0)

.LBB0_855:
	s_or_b64 exec, exec, s[26:27]
	s_mov_b64 s[26:27], exec
	v_mbcnt_lo_u32_b32 v0, s26, 0
	v_mbcnt_hi_u32_b32 v0, s27, v0
	v_cmp_eq_u32_e32 vcc, 0, v0
	s_waitcnt vmcnt(0)
	buffer_inv sc1
	s_waitcnt vmcnt(0)
	s_and_saveexec_b64 s[28:29], vcc
	s_cbranch_execz .LBB0_857
	s_bcnt1_i32_b64 s6, s[26:27]
	v_readlane_b32 s10, v253, 39
	v_mov_b32_e32 v0, s6
	v_readlane_b32 s11, v253, 40
	s_nop 4
	global_atomic_add v141, v0, s[10:11]
